# v9 + grid barrier: the round's last XCD leader bumps every per-XCD release generation directly (other leaders wait on their own XGEN, TOPGEN hop removed)
# speedup vs baseline: 1.0125x; 1.0076x over previous
; __device__ __forceinline__ unsigned xb_ld(unsigned* p)              { return __hip_atomic_load(p, __ATOMIC_RELAXED, __HIP_MEMORY_SCOPE_AGENT); }
; __device__ __forceinline__ unsigned xb_add(unsigned* p, unsigned v) { return __hip_atomic_fetch_add(p, v, __ATOMIC_RELAXED, __HIP_MEMORY_SCOPE_AGENT); }
; #define XB_SPIN(cond, bar) do { unsigned _sp = 0; while (cond) { __builtin_amdgcn_s_sleep(1); \
;     if ((++_sp & 255u) == 0u) { if (xb_ld(&(bar)[XB_TMO])) break; if (_sp > XB_SPIN_CAP) { atomicAdd(&(bar)[XB_TMO], 1u); break; } } } } while (0)
; __device__ __forceinline__ void xcd_barrier(const XcdBarrier& b) {
;     ...
;         const unsigned old = xb_add(&bar[XB_XSUB(b.x)], 1u);
;         const unsigned gen = old / nloc;
;         if (old + 1u == (gen + 1u) * nloc) {
;             __builtin_amdgcn_fence(__ATOMIC_RELEASE, "agent");
;             asm volatile("s_waitcnt vmcnt(0)" ::: "memory");
;             const unsigned og = xb_add(&bar[XB_TOP], 1u);
;             const unsigned tg = og / nx;
;             if (og + 1u == (tg + 1u) * nx) xb_add(&bar[XB_TOPGEN], 1u);
;             else XB_SPIN(xb_ld(&bar[XB_TOPGEN]) == tg, bar);
;             __builtin_amdgcn_fence(__ATOMIC_ACQUIRE, "agent");
;             xb_add(&bar[XB_XGEN(b.x)], 1u);
;             asm volatile("s_waitcnt vmcnt(0)" ::: "memory");
;         } else {
;             XB_SPIN(xb_ld(&bar[XB_XGEN(b.x)]) == gen, bar);
.LBB0_42:
	s_andn2_saveexec_b64 s[4:5], s[4:5]
	s_cbranch_execz .LBB0_62
	s_mov_b64 s[4:5], exec
	buffer_wbl2 sc1
	v_readfirstlane_b32 s98, v3
	s_waitcnt lgkmcnt(0)
	s_waitcnt vmcnt(0)
	v_mbcnt_lo_u32_b32 v3, s4, 0
	v_mbcnt_hi_u32_b32 v3, s5, v3
	v_cmp_eq_u32_e32 vcc, 0, v3
	s_and_saveexec_b64 s[36:37], vcc
	s_cbranch_execz .LBB0_45
	s_bcnt1_i32_b64 s4, s[4:5]
	v_mov_b32_e32 v4, s4
	v_readlane_b32 s4, v252, 26
	v_readlane_b32 s5, v252, 27
	s_nop 4
	global_atomic_add v4, v207, v4, s[4:5] sc0
.LBB0_45:
	s_or_b64 exec, exec, s[36:37]
	v_cvt_f32_u32_e32 v5, v2
	s_waitcnt vmcnt(0)
	v_readfirstlane_b32 s4, v4
	s_mov_b64 s[36:37], -1
	v_rcp_iflag_f32_e32 v5, v5
	v_add_u32_e32 v3, s4, v3
	v_add_u32_e32 v6, 1, v3
	v_readlane_b32 s4, v252, 28
	v_mul_f32_e32 v4, 0x4f7ffffe, v5
	v_cvt_u32_f32_e32 v4, v4
	v_sub_u32_e32 v5, 0, v2
	v_readlane_b32 s5, v252, 29
	v_mul_lo_u32 v5, v5, v4
	v_mul_hi_u32 v5, v4, v5
	v_add_u32_e32 v4, v4, v5
	v_mul_hi_u32 v4, v3, v4
	v_mul_lo_u32 v5, v4, v2
	v_sub_u32_e32 v3, v3, v5
	v_add_u32_e32 v7, 1, v4
	v_cmp_ge_u32_e32 vcc, v3, v2
	v_sub_u32_e32 v5, v3, v2
	s_nop 0
	v_cndmask_b32_e32 v4, v4, v7, vcc
	v_cndmask_b32_e32 v3, v3, v5, vcc
	v_add_u32_e32 v5, 1, v4
	v_cmp_ge_u32_e32 vcc, v3, v2
	s_nop 1
	v_cndmask_b32_e32 v4, v4, v5, vcc
	v_mul_lo_u32 v3, v2, v4
	v_add_u32_e32 v2, v3, v2
	v_cmp_ne_u32_e32 vcc, v6, v2
	v_mov_b64_e32 v[2:3], s[4:5]
	s_and_saveexec_b64 s[4:5], vcc
	s_cbranch_execnz .Lxb_notlast_0
	s_or_b64 exec, exec, s[4:5]
	v_readlane_b32 s28, v252, 26
	v_readlane_b32 s29, v252, 27
	v_mov_b32_e32 v2, 1
	s_add_u32 s28, s28, 0xfffff000
	s_addc_u32 s29, s29, -1
	s_nop 4
	global_atomic_add v207, v2, s[28:29]
	global_atomic_add v207, v2, s[28:29] offset:256
	global_atomic_add v207, v2, s[28:29] offset:512
	global_atomic_add v207, v2, s[28:29] offset:768
	global_atomic_add v207, v2, s[28:29] offset:1024
	global_atomic_add v207, v2, s[28:29] offset:1280
	global_atomic_add v207, v2, s[28:29] offset:1536
	global_atomic_add v207, v2, s[28:29] offset:1792
	global_atomic_add v207, v2, s[28:29] offset:2048
	global_atomic_add v207, v2, s[28:29] offset:2304
	global_atomic_add v207, v2, s[28:29] offset:2560
	global_atomic_add v207, v2, s[28:29] offset:2816
	global_atomic_add v207, v2, s[28:29] offset:3072
	global_atomic_add v207, v2, s[28:29] offset:3328
	global_atomic_add v207, v2, s[28:29] offset:3584
	global_atomic_add v207, v2, s[28:29] offset:3840
	s_branch .LBB0_59
.Lxb_notlast_0:
	v_mov_b32_e32 v4, s98
	v_readlane_b32 s28, v252, 24
	v_readlane_b32 s29, v252, 25
	s_mov_b64 s[38:39], 0
	s_nop 3
	global_load_dword v2, v207, s[28:29] sc1
	s_waitcnt vmcnt(0)
	v_cmp_eq_u32_e32 vcc, v2, v4
	s_and_saveexec_b64 s[36:37], vcc
	s_cbranch_execz .LBB0_56
	s_mov_b32 s34, 1
	s_branch .LBB0_49

; __device__ __forceinline__ unsigned xb_ld(unsigned* p)              { return __hip_atomic_load(p, __ATOMIC_RELAXED, __HIP_MEMORY_SCOPE_AGENT); }
; #define XB_SPIN(cond, bar) do { unsigned _sp = 0; while (cond) { __builtin_amdgcn_s_sleep(1); \
;     if ((++_sp & 255u) == 0u) { if (xb_ld(&(bar)[XB_TMO])) break; if (_sp > XB_SPIN_CAP) { atomicAdd(&(bar)[XB_TMO], 1u); break; } } } } while (0)
; __device__ __forceinline__ void xcd_barrier(const XcdBarrier& b) {
;     ...
;             else XB_SPIN(xb_ld(&bar[XB_TOPGEN]) == tg, bar);
.LBB0_51:
	v_readlane_b32 s28, v252, 24
	v_readlane_b32 s29, v252, 25
	s_add_i32 s34, s34, 1
	s_mov_b64 s[44:45], -1
	s_nop 2
	global_load_dword v2, v207, s[28:29] sc1
	s_waitcnt vmcnt(0)
	v_cmp_ne_u32_e32 vcc, v2, v4
	s_orn2_b64 s[42:43], vcc, exec
	s_branch .LBB0_48

; __device__ __forceinline__ unsigned xb_add(unsigned* p, unsigned v) { return __hip_atomic_fetch_add(p, v, __ATOMIC_RELAXED, __HIP_MEMORY_SCOPE_AGENT); }
; __device__ __forceinline__ void xcd_barrier(const XcdBarrier& b) {
;     ...
;             __builtin_amdgcn_fence(__ATOMIC_ACQUIRE, "agent");
;             xb_add(&bar[XB_XGEN(b.x)], 1u);
;             asm volatile("s_waitcnt vmcnt(0)" ::: "memory");
.LBB0_59:
	s_or_b64 exec, exec, s[4:5]
	s_mov_b64 s[4:5], exec
	v_mbcnt_lo_u32_b32 v2, s4, 0
	v_mbcnt_hi_u32_b32 v2, s5, v2
	v_cmp_eq_u32_e32 vcc, 0, v2
	s_waitcnt vmcnt(0)
	buffer_inv sc1
	s_and_saveexec_b64 s[36:37], vcc
	s_cbranch_execz .LBB0_61
	s_bcnt1_i32_b64 s4, s[4:5]
	v_mov_b32_e32 v2, s4
	v_readlane_b32 s4, v252, 24
	v_readlane_b32 s5, v252, 25
	s_nop 4
	s_nop 0

; __device__ __forceinline__ unsigned xb_ld(unsigned* p)              { return __hip_atomic_load(p, __ATOMIC_RELAXED, __HIP_MEMORY_SCOPE_AGENT); }
; __device__ __forceinline__ unsigned xb_add(unsigned* p, unsigned v) { return __hip_atomic_fetch_add(p, v, __ATOMIC_RELAXED, __HIP_MEMORY_SCOPE_AGENT); }
; #define XB_SPIN(cond, bar) do { unsigned _sp = 0; while (cond) { __builtin_amdgcn_s_sleep(1); \
;     if ((++_sp & 255u) == 0u) { if (xb_ld(&(bar)[XB_TMO])) break; if (_sp > XB_SPIN_CAP) { atomicAdd(&(bar)[XB_TMO], 1u); break; } } } } while (0)
; __device__ __forceinline__ void xcd_barrier(const XcdBarrier& b) {
;     ...
;         const unsigned old = xb_add(&bar[XB_XSUB(b.x)], 1u);
;         const unsigned gen = old / nloc;
;         if (old + 1u == (gen + 1u) * nloc) {
;             __builtin_amdgcn_fence(__ATOMIC_RELEASE, "agent");
;             asm volatile("s_waitcnt vmcnt(0)" ::: "memory");
;             const unsigned og = xb_add(&bar[XB_TOP], 1u);
;             const unsigned tg = og / nx;
;             if (og + 1u == (tg + 1u) * nx) xb_add(&bar[XB_TOPGEN], 1u);
;             else XB_SPIN(xb_ld(&bar[XB_TOPGEN]) == tg, bar);
;             __builtin_amdgcn_fence(__ATOMIC_ACQUIRE, "agent");
;             xb_add(&bar[XB_XGEN(b.x)], 1u);
;             asm volatile("s_waitcnt vmcnt(0)" ::: "memory");
;         } else {
;             XB_SPIN(xb_ld(&bar[XB_XGEN(b.x)]) == gen, bar);
.LBB0_321:
	s_andn2_saveexec_b64 s[4:5], s[4:5]
	s_cbranch_execz .LBB0_341
	s_mov_b64 s[4:5], exec
	buffer_wbl2 sc1
	v_readfirstlane_b32 s98, v3
	s_waitcnt lgkmcnt(0)
	s_waitcnt vmcnt(0)
	v_mbcnt_lo_u32_b32 v3, s4, 0
	v_mbcnt_hi_u32_b32 v3, s5, v3
	v_cmp_eq_u32_e32 vcc, 0, v3
	s_and_saveexec_b64 s[38:39], vcc
	s_cbranch_execz .LBB0_324
	s_bcnt1_i32_b64 s4, s[4:5]
	v_mov_b32_e32 v4, s4
	v_readlane_b32 s4, v252, 26
	v_readlane_b32 s5, v252, 27
	s_nop 4
	global_atomic_add v4, v207, v4, s[4:5] sc0
.LBB0_324:
	s_or_b64 exec, exec, s[38:39]
	s_waitcnt vmcnt(0)
	v_readfirstlane_b32 s4, v4
	v_cvt_f32_u32_e32 v4, v2
	v_sub_u32_e32 v5, 0, v2
	v_add_u32_e32 v3, s4, v3
	v_readlane_b32 s4, v252, 28
	v_rcp_iflag_f32_e32 v4, v4
	v_readlane_b32 s5, v252, 29
	s_mov_b64 s[38:39], -1
	v_mul_f32_e32 v4, 0x4f7ffffe, v4
	v_cvt_u32_f32_e32 v4, v4
	v_mul_lo_u32 v5, v5, v4
	v_mul_hi_u32 v5, v4, v5
	v_add_u32_e32 v4, v4, v5
	v_mul_hi_u32 v4, v3, v4
	v_mul_lo_u32 v5, v4, v2
	v_sub_u32_e32 v5, v3, v5
	v_cmp_ge_u32_e32 vcc, v5, v2
	v_add_u32_e32 v6, 1, v4
	v_add_u32_e32 v3, 1, v3
	v_cndmask_b32_e32 v4, v4, v6, vcc
	v_sub_u32_e32 v6, v5, v2
	v_cndmask_b32_e32 v5, v5, v6, vcc
	v_cmp_ge_u32_e32 vcc, v5, v2
	v_add_u32_e32 v5, 1, v4
	s_nop 0
	v_cndmask_b32_e32 v4, v4, v5, vcc
	v_mul_lo_u32 v5, v2, v4
	v_add_u32_e32 v2, v5, v2
	v_cmp_ne_u32_e32 vcc, v3, v2
	v_mov_b64_e32 v[2:3], s[4:5]
	s_and_saveexec_b64 s[4:5], vcc
	s_cbranch_execnz .Lxb_notlast_1
	s_or_b64 exec, exec, s[4:5]
	v_readlane_b32 s28, v252, 26
	v_readlane_b32 s29, v252, 27
	v_mov_b32_e32 v2, 1
	s_add_u32 s28, s28, 0xfffff000
	s_addc_u32 s29, s29, -1
	s_nop 4
	global_atomic_add v207, v2, s[28:29]
	global_atomic_add v207, v2, s[28:29] offset:256
	global_atomic_add v207, v2, s[28:29] offset:512
	global_atomic_add v207, v2, s[28:29] offset:768
	global_atomic_add v207, v2, s[28:29] offset:1024
	global_atomic_add v207, v2, s[28:29] offset:1280
	global_atomic_add v207, v2, s[28:29] offset:1536
	global_atomic_add v207, v2, s[28:29] offset:1792
	global_atomic_add v207, v2, s[28:29] offset:2048
	global_atomic_add v207, v2, s[28:29] offset:2304
	global_atomic_add v207, v2, s[28:29] offset:2560
	global_atomic_add v207, v2, s[28:29] offset:2816
	global_atomic_add v207, v2, s[28:29] offset:3072
	global_atomic_add v207, v2, s[28:29] offset:3328
	global_atomic_add v207, v2, s[28:29] offset:3584
	global_atomic_add v207, v2, s[28:29] offset:3840
	s_branch .LBB0_338
.Lxb_notlast_1:
	v_mov_b32_e32 v4, s98
	v_readlane_b32 s28, v252, 24
	v_readlane_b32 s29, v252, 25
	s_mov_b64 s[40:41], 0
	s_nop 3
	global_load_dword v2, v207, s[28:29] sc1
	s_waitcnt vmcnt(0)
	v_cmp_eq_u32_e32 vcc, v2, v4
	s_and_saveexec_b64 s[38:39], vcc
	s_cbranch_execz .LBB0_335
	s_mov_b32 s34, 1
	s_branch .LBB0_328

; __device__ __forceinline__ unsigned xb_ld(unsigned* p)              { return __hip_atomic_load(p, __ATOMIC_RELAXED, __HIP_MEMORY_SCOPE_AGENT); }
; #define XB_SPIN(cond, bar) do { unsigned _sp = 0; while (cond) { __builtin_amdgcn_s_sleep(1); \
;     if ((++_sp & 255u) == 0u) { if (xb_ld(&(bar)[XB_TMO])) break; if (_sp > XB_SPIN_CAP) { atomicAdd(&(bar)[XB_TMO], 1u); break; } } } } while (0)
; __device__ __forceinline__ void xcd_barrier(const XcdBarrier& b) {
;     ...
;             else XB_SPIN(xb_ld(&bar[XB_TOPGEN]) == tg, bar);
.LBB0_330:
	v_readlane_b32 s28, v252, 24
	v_readlane_b32 s29, v252, 25
	s_add_i32 s34, s34, 1
	s_mov_b64 s[48:49], -1
	s_nop 2
	global_load_dword v2, v207, s[28:29] sc1
	s_waitcnt vmcnt(0)
	v_cmp_ne_u32_e32 vcc, v2, v4
	s_orn2_b64 s[46:47], vcc, exec
	s_branch .LBB0_327

; __device__ __forceinline__ unsigned xb_add(unsigned* p, unsigned v) { return __hip_atomic_fetch_add(p, v, __ATOMIC_RELAXED, __HIP_MEMORY_SCOPE_AGENT); }
; __device__ __forceinline__ void xcd_barrier(const XcdBarrier& b) {
;     ...
;             __builtin_amdgcn_fence(__ATOMIC_ACQUIRE, "agent");
;             xb_add(&bar[XB_XGEN(b.x)], 1u);
;             asm volatile("s_waitcnt vmcnt(0)" ::: "memory");
.LBB0_338:
	s_or_b64 exec, exec, s[4:5]
	s_mov_b64 s[4:5], exec
	v_mbcnt_lo_u32_b32 v2, s4, 0
	v_mbcnt_hi_u32_b32 v2, s5, v2
	v_cmp_eq_u32_e32 vcc, 0, v2
	s_waitcnt vmcnt(0)
	buffer_inv sc1
	s_and_saveexec_b64 s[38:39], vcc
	s_cbranch_execz .LBB0_340
	s_bcnt1_i32_b64 s4, s[4:5]
	v_mov_b32_e32 v2, s4
	v_readlane_b32 s4, v252, 24
	v_readlane_b32 s5, v252, 25
	s_nop 4
	s_nop 0

; __device__ __forceinline__ unsigned xb_ld(unsigned* p)              { return __hip_atomic_load(p, __ATOMIC_RELAXED, __HIP_MEMORY_SCOPE_AGENT); }
; __device__ __forceinline__ unsigned xb_add(unsigned* p, unsigned v) { return __hip_atomic_fetch_add(p, v, __ATOMIC_RELAXED, __HIP_MEMORY_SCOPE_AGENT); }
; #define XB_SPIN(cond, bar) do { unsigned _sp = 0; while (cond) { __builtin_amdgcn_s_sleep(1); \
;     if ((++_sp & 255u) == 0u) { if (xb_ld(&(bar)[XB_TMO])) break; if (_sp > XB_SPIN_CAP) { atomicAdd(&(bar)[XB_TMO], 1u); break; } } } } while (0)
; __device__ __forceinline__ void xcd_barrier(const XcdBarrier& b) {
;     ...
;         if (old + 1u == (gen + 1u) * nloc) {
;             __builtin_amdgcn_fence(__ATOMIC_RELEASE, "agent");
;             asm volatile("s_waitcnt vmcnt(0)" ::: "memory");
;             const unsigned og = xb_add(&bar[XB_TOP], 1u);
;             const unsigned tg = og / nx;
;             if (og + 1u == (tg + 1u) * nx) xb_add(&bar[XB_TOPGEN], 1u);
;             else XB_SPIN(xb_ld(&bar[XB_TOPGEN]) == tg, bar);
;             __builtin_amdgcn_fence(__ATOMIC_ACQUIRE, "agent");
;             xb_add(&bar[XB_XGEN(b.x)], 1u);
;             asm volatile("s_waitcnt vmcnt(0)" ::: "memory");
;         } else {
;             XB_SPIN(xb_ld(&bar[XB_XGEN(b.x)]) == gen, bar);
.LBB0_961:
	s_or_b64 exec, exec, s[36:37]
	s_waitcnt vmcnt(0)
	v_readfirstlane_b32 s4, v4
	v_cvt_f32_u32_e32 v4, v2
	v_sub_u32_e32 v5, 0, v2
	v_add_u32_e32 v3, s4, v3
	v_readlane_b32 s4, v252, 28
	v_rcp_iflag_f32_e32 v4, v4
	v_readlane_b32 s5, v252, 29
	s_mov_b64 s[36:37], -1
	v_mul_f32_e32 v4, 0x4f7ffffe, v4
	v_cvt_u32_f32_e32 v4, v4
	v_mul_lo_u32 v5, v5, v4
	v_mul_hi_u32 v5, v4, v5
	v_add_u32_e32 v4, v4, v5
	v_mul_hi_u32 v4, v3, v4
	v_mul_lo_u32 v5, v4, v2
	v_sub_u32_e32 v5, v3, v5
	v_cmp_ge_u32_e32 vcc, v5, v2
	v_add_u32_e32 v6, 1, v4
	v_add_u32_e32 v3, 1, v3
	v_cndmask_b32_e32 v4, v4, v6, vcc
	v_sub_u32_e32 v6, v5, v2
	v_cndmask_b32_e32 v5, v5, v6, vcc
	v_cmp_ge_u32_e32 vcc, v5, v2
	v_add_u32_e32 v5, 1, v4
	s_nop 0
	v_cndmask_b32_e32 v4, v4, v5, vcc
	v_mul_lo_u32 v5, v2, v4
	v_add_u32_e32 v2, v5, v2
	v_cmp_ne_u32_e32 vcc, v3, v2
	v_mov_b64_e32 v[2:3], s[4:5]
	s_and_saveexec_b64 s[4:5], vcc
	s_cbranch_execnz .Lxb_notlast_2
	s_or_b64 exec, exec, s[4:5]
	v_readlane_b32 s28, v252, 26
	v_readlane_b32 s29, v252, 27
	v_mov_b32_e32 v2, 1
	s_add_u32 s28, s28, 0xfffff000
	s_addc_u32 s29, s29, -1
	s_nop 4
	global_atomic_add v207, v2, s[28:29]
	global_atomic_add v207, v2, s[28:29] offset:256
	global_atomic_add v207, v2, s[28:29] offset:512
	global_atomic_add v207, v2, s[28:29] offset:768
	global_atomic_add v207, v2, s[28:29] offset:1024
	global_atomic_add v207, v2, s[28:29] offset:1280
	global_atomic_add v207, v2, s[28:29] offset:1536
	global_atomic_add v207, v2, s[28:29] offset:1792
	global_atomic_add v207, v2, s[28:29] offset:2048
	global_atomic_add v207, v2, s[28:29] offset:2304
	global_atomic_add v207, v2, s[28:29] offset:2560
	global_atomic_add v207, v2, s[28:29] offset:2816
	global_atomic_add v207, v2, s[28:29] offset:3072
	global_atomic_add v207, v2, s[28:29] offset:3328
	global_atomic_add v207, v2, s[28:29] offset:3584
	global_atomic_add v207, v2, s[28:29] offset:3840
	s_branch .LBB0_975
